# v55: v37 + static s_setprio 1 for waves 4-7 during the conv loop
# speedup vs baseline: 1.0040x; 1.0018x over previous
; __device__ __forceinline__ void conv_phase(LAS unsigned char* lds, const bf16_t* P, const float* cw, const float* cb, const float* ng, const float* nb, bf16_t* CAT, int bid, int G, const int tid) {
;     ...
;     if (bid < 4096) CONV_LOAD(bid);
; __global__ void __launch_bounds__(512, 2) mk_fwd(Params p) {
;     ...
;             conv_phase(lds, Pb, INP(19), INP(20), INP(21), INP(22), H, bid, G, tid);
.LBB0_161:
	s_load_dwordx2 s[4:5], s[0:1], 0x98
	s_waitcnt lgkmcnt(0)
	s_load_dwordx2 s[6:7], s[0:1], 0xa0
	s_waitcnt lgkmcnt(0)
	s_load_dwordx2 s[20:21], s[0:1], 0xa8
	s_waitcnt lgkmcnt(0)
	s_load_dwordx2 s[30:31], s[0:1], 0xb0
	s_waitcnt lgkmcnt(0)
	s_cmpk_gt_i32 s12, 0xfff
	s_cbranch_scc1 .LBB0_186
	s_mov_b32 s63, -1
	v_readfirstlane_b32 s64, v179
	s_cmpk_lt_u32 s64, 0x100
	s_cbranch_scc1 .Lconv_prio_skip
	s_setprio 1
.Lconv_prio_skip:
	s_and_b32 s3, s50, 0x7c0
	s_lshl_b32 s15, s12, 8
	s_sub_i32 s13, s3, 30
	s_and_b32 s3, s50, 0xfffff800
	s_and_b32 s15, s15, 0x700
	v_lshlrev_b32_e32 v30, 3, v238
	v_ashrrev_i32_e32 v36, 4, v238
	s_add_u32 s34, s10, s15
	v_and_b32_e32 v26, 0x78, v30
	v_add_u32_e32 v5, s13, v36
	s_movk_i32 s15, 0x5e0
	v_mov_b32_e32 v2, v177
	v_mov_b32_e32 v3, v177
	s_addc_u32 s35, s11, 0
	v_lshlrev_b32_e32 v176, 1, v26
	v_cmp_gt_i32_e64 s[38:39], s15, v238
	v_cmp_lt_i32_e32 vcc, -1, v5
	v_mov_b32_e32 v0, v177
	v_mov_b32_e32 v1, v177
	v_mov_b64_e32 v[14:15], v[2:3]
	v_lshl_add_u64 v[24:25], s[34:35], 0, v[176:177]
	s_and_b64 s[40:41], s[38:39], vcc
	v_mov_b32_e32 v4, 0
	v_mov_b64_e32 v[12:13], v[0:1]
	v_mov_b32_e32 v8, 0
	v_mov_b32_e32 v9, 0
	v_mov_b32_e32 v10, 0
	v_mov_b32_e32 v11, 0
	s_and_saveexec_b64 s[34:35], s[40:41]
	s_cbranch_execz .LBB0_164
	v_add_u32_e32 v5, s3, v5
	v_mad_i64_i32 v[6:7], s[40:41], v5, s48, v[24:25]
	v_add_co_u32_e32 v12, vcc, 0x1000, v6
	s_nop 1
	v_addc_co_u32_e32 v13, vcc, 0, v7, vcc
	global_load_dwordx4 v[8:11], v[6:7], off offset:2176
	s_nop 0
	global_load_dwordx4 v[12:15], v[12:13], off offset:128

; __device__ __forceinline__ void conv_phase(LAS unsigned char* lds, const bf16_t* P, const float* cw, const float* cb, const float* ng, const float* nb, bf16_t* CAT, int bid, int G, const int tid) {
;     ...
;     __syncthreads();
.LBB0_186:
	s_setprio 0
	s_waitcnt lgkmcnt(0)
	s_barrier
	s_mov_b64 s[40:41], -1
